# attention item table re-dealt assuming costlier skipped subtiles (first-skip 0.85, later 0.5 of a full subtile)
# speedup vs baseline: 1.0079x; 1.0079x over previous
.Ltbl:
	s_and_b32 s0, s73, 15
	s_mov_b32 s100, 0x401c5b7c
	s_cmp_eq_u32 s0, 1
	s_cselect_b32 s100, 0x4051cc24, s100
	s_cmp_eq_u32 s0, 2
	s_cselect_b32 s100, 0x40261e2e, s100
	s_cmp_eq_u32 s0, 3
	s_cselect_b32 s100, 0x405939b2, s100
	s_cmp_eq_u32 s0, 4
	s_cselect_b32 s100, 0x400a077e, s100
	s_cmp_eq_u32 s0, 5
	s_cselect_b32 s100, 0x4018f8ff, s100
	s_cmp_eq_u32 s0, 6
	s_cselect_b32 s100, 0x4035fa6f, s100
	s_cmp_eq_u32 s0, 7
	s_cselect_b32 s100, 0x4029567d, s100
	s_cmp_eq_u32 s0, 8
	s_cselect_b32 s100, 0x40218ab3, s100
	s_cmp_eq_u32 s0, 9
	s_cselect_b32 s100, 0x40057e77, s100
	s_cmp_eq_u32 s0, 10
	s_cselect_b32 s100, 0x4001e8b4, s100
	s_cmp_eq_u32 s0, 11
	s_cselect_b32 s100, 0x403909f5, s100
	s_cmp_eq_u32 s0, 12
	s_cselect_b32 s100, 0x402dac7a, s100
	s_cmp_eq_u32 s0, 13
	s_cselect_b32 s100, 0x404686eb, s100
	s_cmp_eq_u32 s0, 14
	s_cselect_b32 s100, 0x400ccb36, s100
	s_cmp_eq_u32 s0, 15
	s_cselect_b32 s100, 0x4011297b, s100
	s_mov_b32 s74, 0
